# GEMM modes 0/2: k-tile 2 of the next tile also loaded before the epilogue stores (into dead accumulator registers), first two K iterations no longer wait behind the store drain
# speedup vs baseline: 1.0058x; 1.0058x over previous
; #define G5_LOAD(k0)                                                                 \
;   {                                                                                 \
;     _Pragma("unroll") for (int i_ = 0; i_ < 4; ++i_) ra[i_] = ldg16(Ap + (size_t)(i_ * 64) * lda + (k0)); \
;     _Pragma("unroll") for (int i_ = 0; i_ < 4; ++i_) rb[i_] = ldg16(Bp + (size_t)(i_ * 64) * ldb + (k0)); \
;   }
; #define G5_STORE(s)                                                                 \
;   {                                                                                 \
;     _Pragma("unroll") for (int i_ = 0; i_ < 4; ++i_) *(u32x4*)(Sw + (s) * STG + i_ * 64 * GS) = ra[i_]; \
;     _Pragma("unroll") for (int i_ = 0; i_ < 4; ++i_) *(u32x4*)(Sw + (s) * STG + 256 * GS + i_ * 64 * GS) = rb[i_]; \
;   }
; template <typename Epi>
; DI void gemm_tile512(const u16* __restrict__ A, int lda, const u16* __restrict__ Bt, int ldb, int K, char* lds_all, Epi epi) {
;     ...
;   const int nk = K >> 6;
;   __syncthreads();
;   G5_LOAD(0);
;   G5_STORE(0);
;   G5_LOAD(64);
;   __syncthreads();
; DI void gemm_phase(const Params& p, int layer, int mode, int nrows, char* lds_all) {
;     ...
;   for (int i = jb;; i += nj) {
;     const int srl = i / per, rem = i - srl * per;
;     const int sr = xcd + nx * srl;
;     if (sr >= nsr) break;
;     const int tn = rem >> 1, tm = sr * 2 + (rem & 1);
;     const int m0 = tm * 256, n0 = tn * 256;
;     gemm_tile512(A + (size_t)m0 * lda, lda, Bt + (size_t)n0 * ldb, ldb, K, lds_all, [&](int half) {
.LBB0_198:
	s_mul_i32 s6, s4, 0xffffffea
	s_lshl_b32 s11, s5, 9
	s_lshl_b32 s5, s16, 8
	s_add_i32 s6, s6, s16
	s_and_b32 s5, s5, 0x100
	s_or_b32 s17, s5, s11
	s_lshl_b32 s5, s6, 7
	s_and_b32 s18, s5, 0xffffff00
	s_mul_i32 s6, s17, 0x900
	v_readlane_b32 s7, v250, 46
	s_mul_hi_i32 s5, s17, 0x900
	s_add_u32 s6, s7, s6
	v_readlane_b32 s7, v250, 47
	s_addc_u32 s7, s7, s5
	s_mul_i32 s8, s18, 0x900
	s_mul_hi_i32 s5, s18, 0x900
	s_add_u32 s8, s2, s8
	s_addc_u32 s9, s3, s5
	s_mov_b64 s[98:99], s[6:7]
	s_mov_b64 s[100:101], s[8:9]
	v_lshrrev_b32_e32 v239, 3, v165
	v_and_b32_e32 v0, 7, v165
	v_mul_u32_u24_e32 v206, 0x900, v239
	v_lshl_add_u32 v206, v0, 4, v206
	v_add_u32_e32 v207, 0x24000, v206
	v_add_u32_e32 v208, 0x48000, v206
	v_add_u32_e32 v238, 0x6c000, v206
	global_load_dwordx4 v[130:133], v206, s[98:99]
	global_load_dwordx4 v[134:137], v207, s[98:99]
	global_load_dwordx4 v[138:141], v208, s[98:99]
	global_load_dwordx4 v[142:145], v238, s[98:99]
	global_load_dwordx4 v[146:149], v206, s[100:101]
	global_load_dwordx4 v[150:153], v207, s[100:101]
	global_load_dwordx4 v[154:157], v208, s[100:101]
	global_load_dwordx4 v[158:161], v238, s[100:101]
	global_load_dwordx4 v[218:221], v206, s[98:99] offset:128
	global_load_dwordx4 v[222:225], v207, s[98:99] offset:128
	global_load_dwordx4 v[226:229], v208, s[98:99] offset:128
	global_load_dwordx4 v[230:233], v238, s[98:99] offset:128
	global_load_dwordx4 v[166:169], v206, s[100:101] offset:128
	global_load_dwordx4 v[170:173], v207, s[100:101] offset:128
	global_load_dwordx4 v[174:177], v208, s[100:101] offset:128
	global_load_dwordx4 v[190:193], v238, s[100:101] offset:128
	s_add_u32 s98, s98, 0x100
	s_addc_u32 s99, s99, 0
	s_add_u32 s100, s100, 0x100
	s_addc_u32 s101, s101, 0
	global_load_dwordx4 v[66:69], v206, s[98:99]
	global_load_dwordx4 v[70:73], v207, s[98:99]
	global_load_dwordx4 v[74:77], v208, s[98:99]
	global_load_dwordx4 v[78:81], v238, s[98:99]
	global_load_dwordx4 v[82:85], v206, s[100:101]
	global_load_dwordx4 v[86:89], v207, s[100:101]
	global_load_dwordx4 v[90:93], v208, s[100:101]
	global_load_dwordx4 v[94:97], v238, s[100:101]
	v_lshrrev_b32_e32 v239, 3, v165
	v_and_b32_e32 v0, 7, v165
	v_mul_u32_u24_e32 v180, 0x90, v239
	v_lshl_add_u32 v180, v0, 4, v180
	v_and_b32_e32 v239, 31, v165
	v_bfe_u32 v0, v165, 5, 1
	v_lshrrev_b32_e32 v179, 8, v165
	v_lshl_or_b32 v178, v179, 7, v239
	v_mul_u32_u24_e32 v178, 0x90, v178
	v_lshl_add_u32 v178, v0, 4, v178
	v_bfe_u32 v179, v165, 6, 2
	v_lshl_or_b32 v179, v179, 6, v239
	v_mul_u32_u24_e32 v179, 0x90, v179
	v_lshl_add_u32 v179, v0, 4, v179
	s_mov_b32 s12, 0x12000
	s_mov_b32 s13, 12
	s_barrier
	s_waitcnt vmcnt(23)
	ds_write_b128 v180, v[130:133]
	s_waitcnt vmcnt(22)
	ds_write_b128 v180, v[134:137] offset:9216
	s_waitcnt vmcnt(21)
	ds_write_b128 v180, v[138:141] offset:18432
	s_waitcnt vmcnt(20)
	ds_write_b128 v180, v[142:145] offset:27648
	s_waitcnt vmcnt(19)
	ds_write_b128 v180, v[146:149] offset:36864
	s_waitcnt vmcnt(18)
	ds_write_b128 v180, v[150:153] offset:46080
	s_waitcnt vmcnt(17)
	ds_write_b128 v180, v[154:157] offset:55296
	s_waitcnt vmcnt(16)
	ds_write_b128 v180, v[158:161] offset:64512
	v_add_u32_e32 v180, 0x12000, v180
	s_waitcnt vmcnt(15)
	ds_write_b128 v180, v[218:221]
	s_waitcnt vmcnt(14)
	ds_write_b128 v180, v[222:225] offset:9216
	s_waitcnt vmcnt(13)
	ds_write_b128 v180, v[226:229] offset:18432
	s_waitcnt vmcnt(12)
	ds_write_b128 v180, v[230:233] offset:27648
	s_waitcnt vmcnt(11)
	ds_write_b128 v180, v[166:169] offset:36864
	s_waitcnt vmcnt(10)
	ds_write_b128 v180, v[170:173] offset:46080
	s_waitcnt vmcnt(9)
	ds_write_b128 v180, v[174:177] offset:55296
	s_waitcnt vmcnt(8)
	ds_write_b128 v180, v[190:193] offset:64512
	s_waitcnt vmcnt(0)
	v_mov_b64_e32 v[130:131], v[66:67]
	v_mov_b64_e32 v[132:133], v[68:69]
	v_mov_b64_e32 v[134:135], v[70:71]
	v_mov_b64_e32 v[136:137], v[72:73]
	v_mov_b64_e32 v[138:139], v[74:75]
	v_mov_b64_e32 v[140:141], v[76:77]
	v_mov_b64_e32 v[142:143], v[78:79]
	v_mov_b64_e32 v[144:145], v[80:81]
	v_mov_b64_e32 v[146:147], v[82:83]
	v_mov_b64_e32 v[148:149], v[84:85]
	v_mov_b64_e32 v[150:151], v[86:87]
	v_mov_b64_e32 v[152:153], v[88:89]
	v_mov_b64_e32 v[154:155], v[90:91]
	v_mov_b64_e32 v[156:157], v[92:93]
	v_mov_b64_e32 v[158:159], v[94:95]
	v_mov_b64_e32 v[160:161], v[96:97]
	s_waitcnt lgkmcnt(0)
	s_branch .Lg3_k_m0
.Lg3_start_m0:
	v_lshrrev_b32_e32 v239, 3, v165
	v_and_b32_e32 v0, 7, v165
	v_mul_u32_u24_e32 v180, 0x90, v239
	v_lshl_add_u32 v180, v0, 4, v180
	v_and_b32_e32 v239, 31, v165
	v_bfe_u32 v0, v165, 5, 1
	v_lshrrev_b32_e32 v179, 8, v165
	v_lshl_or_b32 v178, v179, 7, v239
	v_mul_u32_u24_e32 v178, 0x90, v178
	v_lshl_add_u32 v178, v0, 4, v178
	v_bfe_u32 v179, v165, 6, 2
	v_lshl_or_b32 v179, v179, 6, v239
	v_mul_u32_u24_e32 v179, 0x90, v179
	v_lshl_add_u32 v179, v0, 4, v179
	s_mov_b32 s12, 0x12000
	s_mov_b32 s13, 12
	s_barrier
	s_waitcnt vmcnt(39)
	ds_write_b128 v180, v[130:133]
	s_waitcnt vmcnt(38)
	ds_write_b128 v180, v[134:137] offset:9216
	s_waitcnt vmcnt(37)
	ds_write_b128 v180, v[138:141] offset:18432
	s_waitcnt vmcnt(36)
	ds_write_b128 v180, v[142:145] offset:27648
	s_waitcnt vmcnt(35)
	ds_write_b128 v180, v[146:149] offset:36864
	s_waitcnt vmcnt(34)
	ds_write_b128 v180, v[150:153] offset:46080
	s_waitcnt vmcnt(33)
	ds_write_b128 v180, v[154:157] offset:55296
	s_waitcnt vmcnt(32)
	ds_write_b128 v180, v[158:161] offset:64512
	v_add_u32_e32 v180, 0x12000, v180
	s_waitcnt vmcnt(31)
	ds_write_b128 v180, v[218:221]
	s_waitcnt vmcnt(30)
	ds_write_b128 v180, v[222:225] offset:9216
	s_waitcnt vmcnt(29)
	ds_write_b128 v180, v[226:229] offset:18432
	s_waitcnt vmcnt(28)
	ds_write_b128 v180, v[230:233] offset:27648
	s_waitcnt vmcnt(27)
	ds_write_b128 v180, v[166:169] offset:36864
	s_waitcnt vmcnt(26)
	ds_write_b128 v180, v[170:173] offset:46080
	s_waitcnt vmcnt(25)
	ds_write_b128 v180, v[174:177] offset:55296
	s_waitcnt vmcnt(24)
	ds_write_b128 v180, v[190:193] offset:64512
	s_waitcnt vmcnt(16)
	v_mov_b64_e32 v[130:131], v[66:67]
	v_mov_b64_e32 v[132:133], v[68:69]
	v_mov_b64_e32 v[134:135], v[70:71]
	v_mov_b64_e32 v[136:137], v[72:73]
	v_mov_b64_e32 v[138:139], v[74:75]
	v_mov_b64_e32 v[140:141], v[76:77]
	v_mov_b64_e32 v[142:143], v[78:79]
	v_mov_b64_e32 v[144:145], v[80:81]
	v_mov_b64_e32 v[146:147], v[82:83]
	v_mov_b64_e32 v[148:149], v[84:85]
	v_mov_b64_e32 v[150:151], v[86:87]
	v_mov_b64_e32 v[152:153], v[88:89]
	v_mov_b64_e32 v[154:155], v[90:91]
	v_mov_b64_e32 v[156:157], v[92:93]
	v_mov_b64_e32 v[158:159], v[94:95]
	v_mov_b64_e32 v[160:161], v[96:97]
	s_waitcnt lgkmcnt(0)
; #define G5_LOAD(k0)                                                                 \
;   {                                                                                 \
;     _Pragma("unroll") for (int i_ = 0; i_ < 4; ++i_) ra[i_] = ldg16(Ap + (size_t)(i_ * 64) * lda + (k0)); \
;     _Pragma("unroll") for (int i_ = 0; i_ < 4; ++i_) rb[i_] = ldg16(Bp + (size_t)(i_ * 64) * ldb + (k0)); \
;   }
; #define G5_STORE(s)                                                                 \
;   {                                                                                 \
;     _Pragma("unroll") for (int i_ = 0; i_ < 4; ++i_) *(u32x4*)(Sw + (s) * STG + i_ * 64 * GS) = ra[i_]; \
;     _Pragma("unroll") for (int i_ = 0; i_ < 4; ++i_) *(u32x4*)(Sw + (s) * STG + 256 * GS + i_ * 64 * GS) = rb[i_]; \
;   }
; template <typename Epi>
; DI void gemm_tile512(const u16* __restrict__ A, int lda, const u16* __restrict__ Bt, int ldb, int K, char* lds_all, Epi epi) {
;     ...
;   for (int kt = 0; kt + 2 < nk; ++kt) {
;     const int cur = kt & 1;
;     G5_COMPUTE(cur);
;     G5_STORE(cur ^ 1);
;     G5_LOAD((kt + 2) << 6);
;     __syncthreads();
;   }
.Lg3_k_m0:
	s_barrier
	ds_read_b128 v[194:197], v179 offset:36864
	ds_read_b128 v[166:169], v178
	ds_read_b128 v[198:201], v179 offset:41472
	ds_read_b128 v[170:173], v178 offset:4608
	ds_read_b128 v[174:177], v178 offset:9216
	ds_read_b128 v[190:193], v178 offset:13824
	s_waitcnt lgkmcnt(4)
	v_mfma_f32_32x32x16_bf16 v[114:129], v[194:197], v[166:169], 0
	ds_read_b128 v[234:237], v179 offset:36896
	s_waitcnt lgkmcnt(4)
	v_mfma_f32_32x32x16_bf16 v[98:113], v[198:201], v[166:169], 0
	ds_read_b128 v[218:221], v178 offset:32
	s_waitcnt lgkmcnt(4)
	v_mfma_f32_32x32x16_bf16 v[82:97], v[194:197], v[170:173], 0
	ds_read_b128 v[202:205], v179 offset:41504
	v_mfma_f32_32x32x16_bf16 v[66:81], v[198:201], v[170:173], 0
	ds_read_b128 v[222:225], v178 offset:4640
	s_waitcnt lgkmcnt(5)
	v_mfma_f32_32x32x16_bf16 v[50:65], v[194:197], v[174:177], 0
	ds_read_b128 v[226:229], v178 offset:9248
	v_mfma_f32_32x32x16_bf16 v[34:49], v[198:201], v[174:177], 0
	ds_read_b128 v[230:233], v178 offset:13856
	s_waitcnt lgkmcnt(6)
	v_mfma_f32_32x32x16_bf16 v[18:33], v[194:197], v[190:193], 0
	v_mfma_f32_32x32x16_bf16 v[2:17], v[198:201], v[190:193], 0
	s_waitcnt lgkmcnt(4)
	v_mfma_f32_32x32x16_bf16 v[114:129], v[234:237], v[218:221], v[114:129]
	ds_read_b128 v[194:197], v179 offset:36928
	s_waitcnt lgkmcnt(4)
	v_mfma_f32_32x32x16_bf16 v[98:113], v[202:205], v[218:221], v[98:113]
	ds_read_b128 v[166:169], v178 offset:64
	s_waitcnt lgkmcnt(4)
	v_mfma_f32_32x32x16_bf16 v[82:97], v[234:237], v[222:225], v[82:97]
	ds_read_b128 v[198:201], v179 offset:41536
	v_mfma_f32_32x32x16_bf16 v[66:81], v[202:205], v[222:225], v[66:81]
	ds_read_b128 v[170:173], v178 offset:4672
	s_waitcnt lgkmcnt(5)
	v_mfma_f32_32x32x16_bf16 v[50:65], v[234:237], v[226:229], v[50:65]
	ds_read_b128 v[174:177], v178 offset:9280
	v_mfma_f32_32x32x16_bf16 v[34:49], v[202:205], v[226:229], v[34:49]
	ds_read_b128 v[190:193], v178 offset:13888
	s_waitcnt lgkmcnt(6)
	v_mfma_f32_32x32x16_bf16 v[18:33], v[234:237], v[230:233], v[18:33]
	v_mfma_f32_32x32x16_bf16 v[2:17], v[202:205], v[230:233], v[2:17]
	v_subrev_u32_e32 v180, s12, v180
	s_waitcnt lgkmcnt(4)
	v_mfma_f32_32x32x16_bf16 v[114:129], v[194:197], v[166:169], v[114:129]
	ds_read_b128 v[234:237], v179 offset:36960
	s_waitcnt lgkmcnt(4)
	v_mfma_f32_32x32x16_bf16 v[98:113], v[198:201], v[166:169], v[98:113]
	ds_read_b128 v[218:221], v178 offset:96
	s_waitcnt lgkmcnt(4)
	v_mfma_f32_32x32x16_bf16 v[82:97], v[194:197], v[170:173], v[82:97]
	ds_read_b128 v[202:205], v179 offset:41568
	v_mfma_f32_32x32x16_bf16 v[66:81], v[198:201], v[170:173], v[66:81]
	ds_read_b128 v[222:225], v178 offset:4704
	s_waitcnt lgkmcnt(5)
	v_mfma_f32_32x32x16_bf16 v[50:65], v[194:197], v[174:177], v[50:65]
	ds_read_b128 v[226:229], v178 offset:9312
	v_mfma_f32_32x32x16_bf16 v[34:49], v[198:201], v[174:177], v[34:49]
	ds_read_b128 v[230:233], v178 offset:13920
	v_add_u32_e32 v178, s12, v178
	v_add_u32_e32 v179, s12, v179
	s_waitcnt lgkmcnt(6)
	v_mfma_f32_32x32x16_bf16 v[18:33], v[194:197], v[190:193], v[18:33]
	v_mfma_f32_32x32x16_bf16 v[2:17], v[198:201], v[190:193], v[2:17]
	s_sub_u32 s12, 0, s12
	s_add_u32 s98, s98, 0x80
	s_addc_u32 s99, s99, 0
	s_add_u32 s100, s100, 0x80
	s_addc_u32 s101, s101, 0
	s_waitcnt lgkmcnt(0)
	s_barrier
; #define G5_LOAD(k0)                                                                 \
;   {                                                                                 \
;     _Pragma("unroll") for (int i_ = 0; i_ < 4; ++i_) ra[i_] = ldg16(Ap + (size_t)(i_ * 64) * lda + (k0)); \
;     _Pragma("unroll") for (int i_ = 0; i_ < 4; ++i_) rb[i_] = ldg16(Bp + (size_t)(i_ * 64) * ldb + (k0)); \
;   }
; #define G5_STORE(s)                                                                 \
;   {                                                                                 \
;     _Pragma("unroll") for (int i_ = 0; i_ < 4; ++i_) *(u32x4*)(Sw + (s) * STG + i_ * 64 * GS) = ra[i_]; \
;     _Pragma("unroll") for (int i_ = 0; i_ < 4; ++i_) *(u32x4*)(Sw + (s) * STG + 256 * GS + i_ * 64 * GS) = rb[i_]; \
;   }
; template <typename Epi>
; DI void gemm_tile512(const u16* __restrict__ A, int lda, const u16* __restrict__ Bt, int ldb, int K, char* lds_all, Epi epi) {
;     ...
;   for (int kt = 0; kt + 2 < nk; ++kt) {
;     const int cur = kt & 1;
;     G5_COMPUTE(cur);
;     G5_STORE(cur ^ 1);
;     G5_LOAD((kt + 2) << 6);
;     __syncthreads();
;   }
	ds_read_b128 v[194:197], v179 offset:36864
	ds_read_b128 v[166:169], v178
	v_mfma_f32_32x32x16_bf16 v[114:129], v[234:237], v[218:221], v[114:129]
	ds_read_b128 v[198:201], v179 offset:41472
	v_mfma_f32_32x32x16_bf16 v[98:113], v[202:205], v[218:221], v[98:113]
	ds_read_b128 v[170:173], v178 offset:4608
	v_mfma_f32_32x32x16_bf16 v[82:97], v[234:237], v[222:225], v[82:97]
	ds_read_b128 v[174:177], v178 offset:9216
	v_mfma_f32_32x32x16_bf16 v[66:81], v[202:205], v[222:225], v[66:81]
	ds_read_b128 v[190:193], v178 offset:13824
	v_mfma_f32_32x32x16_bf16 v[50:65], v[234:237], v[226:229], v[50:65]
	v_mfma_f32_32x32x16_bf16 v[34:49], v[202:205], v[226:229], v[34:49]
	v_mfma_f32_32x32x16_bf16 v[18:33], v[234:237], v[230:233], v[18:33]
	v_mfma_f32_32x32x16_bf16 v[2:17], v[202:205], v[230:233], v[2:17]
	s_waitcnt lgkmcnt(4)
	v_mfma_f32_32x32x16_bf16 v[114:129], v[194:197], v[166:169], v[114:129]
	ds_read_b128 v[234:237], v179 offset:36896
	s_waitcnt lgkmcnt(4)
	v_mfma_f32_32x32x16_bf16 v[98:113], v[198:201], v[166:169], v[98:113]
	ds_read_b128 v[218:221], v178 offset:32
	ds_write_b128 v180, v[130:133]
	global_load_dwordx4 v[130:133], v206, s[98:99]
	s_waitcnt lgkmcnt(5)
	v_mfma_f32_32x32x16_bf16 v[82:97], v[194:197], v[170:173], v[82:97]
	ds_read_b128 v[202:205], v179 offset:41504
	v_mfma_f32_32x32x16_bf16 v[66:81], v[198:201], v[170:173], v[66:81]
	ds_read_b128 v[222:225], v178 offset:4640
	ds_write_b128 v180, v[134:137] offset:9216
	global_load_dwordx4 v[134:137], v207, s[98:99]
	s_waitcnt lgkmcnt(7)
	v_mfma_f32_32x32x16_bf16 v[50:65], v[194:197], v[174:177], v[50:65]
	ds_read_b128 v[226:229], v178 offset:9248
	v_mfma_f32_32x32x16_bf16 v[34:49], v[198:201], v[174:177], v[34:49]
	ds_read_b128 v[230:233], v178 offset:13856
	ds_write_b128 v180, v[138:141] offset:18432
	global_load_dwordx4 v[138:141], v208, s[98:99]
	s_waitcnt lgkmcnt(9)
	v_mfma_f32_32x32x16_bf16 v[18:33], v[194:197], v[190:193], v[18:33]
	v_mfma_f32_32x32x16_bf16 v[2:17], v[198:201], v[190:193], v[2:17]
	ds_write_b128 v180, v[142:145] offset:27648
	global_load_dwordx4 v[142:145], v238, s[98:99]
	s_waitcnt lgkmcnt(8)
	v_mfma_f32_32x32x16_bf16 v[114:129], v[234:237], v[218:221], v[114:129]
	ds_read_b128 v[194:197], v179 offset:36928
	s_waitcnt lgkmcnt(7)
	v_mfma_f32_32x32x16_bf16 v[98:113], v[202:205], v[218:221], v[98:113]
	ds_read_b128 v[166:169], v178 offset:64
	ds_write_b128 v180, v[146:149] offset:36864
	global_load_dwordx4 v[146:149], v206, s[100:101]
	s_waitcnt lgkmcnt(8)
	v_mfma_f32_32x32x16_bf16 v[82:97], v[234:237], v[222:225], v[82:97]
	ds_read_b128 v[198:201], v179 offset:41536
	v_mfma_f32_32x32x16_bf16 v[66:81], v[202:205], v[222:225], v[66:81]
	ds_read_b128 v[170:173], v178 offset:4672
	ds_write_b128 v180, v[150:153] offset:46080
	global_load_dwordx4 v[150:153], v207, s[100:101]
	s_waitcnt lgkmcnt(9)
	v_mfma_f32_32x32x16_bf16 v[50:65], v[234:237], v[226:229], v[50:65]
	ds_read_b128 v[174:177], v178 offset:9280
	v_mfma_f32_32x32x16_bf16 v[34:49], v[202:205], v[226:229], v[34:49]
	ds_read_b128 v[190:193], v178 offset:13888
	ds_write_b128 v180, v[154:157] offset:55296
	global_load_dwordx4 v[154:157], v208, s[100:101]
	s_waitcnt lgkmcnt(11)
	v_mfma_f32_32x32x16_bf16 v[18:33], v[234:237], v[230:233], v[18:33]
	v_mfma_f32_32x32x16_bf16 v[2:17], v[202:205], v[230:233], v[2:17]
	ds_write_b128 v180, v[158:161] offset:64512
	global_load_dwordx4 v[158:161], v238, s[100:101]
	v_subrev_u32_e32 v180, s12, v180
	s_waitcnt lgkmcnt(8)
	v_mfma_f32_32x32x16_bf16 v[114:129], v[194:197], v[166:169], v[114:129]
	ds_read_b128 v[234:237], v179 offset:36960
	s_waitcnt lgkmcnt(7)
	v_mfma_f32_32x32x16_bf16 v[98:113], v[198:201], v[166:169], v[98:113]
	ds_read_b128 v[218:221], v178 offset:96
	s_waitcnt lgkmcnt(7)
	v_mfma_f32_32x32x16_bf16 v[82:97], v[194:197], v[170:173], v[82:97]
	ds_read_b128 v[202:205], v179 offset:41568
	v_mfma_f32_32x32x16_bf16 v[66:81], v[198:201], v[170:173], v[66:81]
	ds_read_b128 v[222:225], v178 offset:4704
	s_waitcnt lgkmcnt(7)
	v_mfma_f32_32x32x16_bf16 v[50:65], v[194:197], v[174:177], v[50:65]
	ds_read_b128 v[226:229], v178 offset:9312
	v_mfma_f32_32x32x16_bf16 v[34:49], v[198:201], v[174:177], v[34:49]
	ds_read_b128 v[230:233], v178 offset:13920
	v_add_u32_e32 v178, s12, v178
	v_add_u32_e32 v179, s12, v179
	s_waitcnt lgkmcnt(8)
	v_mfma_f32_32x32x16_bf16 v[18:33], v[194:197], v[190:193], v[18:33]
	v_mfma_f32_32x32x16_bf16 v[2:17], v[198:201], v[190:193], v[2:17]
	s_sub_u32 s12, 0, s12
	s_add_u32 s98, s98, 0x80
	s_addc_u32 s99, s99, 0
	s_add_u32 s100, s100, 0x80
	s_addc_u32 s101, s101, 0
	s_waitcnt lgkmcnt(0)

; DI int crow(int reg, int h) { return (reg & 3) + 8 * (reg >> 2) + 4 * h; }
; template <typename Epi>
; DI void gemm_tile512(const u16* __restrict__ A, int lda, const u16* __restrict__ Bt, int ldb, int K, char* lds_all, Epi epi) {
;     ...
; #pragma unroll 1
;   for (int half = 0; half < 2; ++half) {
;     __syncthreads();
;     if (wm == half) {
; #pragma unroll
;       for (int i = 0; i < 4; ++i)
; #pragma unroll
;         for (int j = 0; j < 2; ++j)
; #pragma unroll
;           for (int g = 0; g < 16; ++g) Cs[(i * 32 + crow(g, h)) * CSW + wn * 64 + j * 32 + r] = acc[i][j][g];
;     }
;     __syncthreads();
;     epi(half);
;   }
; DI void gemm_phase(const Params& p, int layer, int mode, int nrows, char* lds_all) {
;     ...
;       if (mode == 0 || mode == 2) {
;         for (int idx = tid; idx < 128 * 32; idx += 512) {
;           const int rr = idx >> 5, c8 = (idx & 31) * 8;
;           const int row = m0 + half * 128 + rr, col = n0 + c8;
;           const float4 v0 = *(const float4*)(Cs + rr * CSW + c8), v1 = *(const float4*)(Cs + rr * CSW + c8 + 4);
;           if (mode == 0) {
;             uint4 o;
;             o.x = pack2(v0.x, v0.y); o.y = pack2(v0.z, v0.w); o.z = pack2(v1.x, v1.y); o.w = pack2(v1.z, v1.w);
;             *(uint4*)((u16*)(p.ws + O_Z) + (size_t)row * ZW + col) = o;
.Lg3_nonext_m0:
	v_lshrrev_b32_e32 v237, 8, v165
	v_and_b32_e32 v194, 31, v165
	v_lshl_or_b32 v237, v237, 7, v194
	v_mul_u32_u24_e32 v236, 0x208, v237
	v_bfe_u32 v237, v165, 6, 2
	v_bfe_u32 v194, v165, 5, 1
	v_lshlrev_b32_e32 v237, 7, v237
	v_lshl_or_b32 v237, v194, 3, v237
	v_add_u32_e32 v236, v236, v237
	v_cvt_pk_bf16_f32 v114, v114, v115
	v_cvt_pk_bf16_f32 v115, v116, v117
	v_cvt_pk_bf16_f32 v118, v118, v119
	v_cvt_pk_bf16_f32 v119, v120, v121
	v_cvt_pk_bf16_f32 v122, v122, v123
	v_cvt_pk_bf16_f32 v123, v124, v125
	v_cvt_pk_bf16_f32 v126, v126, v127
	v_cvt_pk_bf16_f32 v127, v128, v129
	s_barrier
	ds_write_b64 v236, v[114:115]
	ds_write_b64 v236, v[118:119] offset:16
	ds_write_b64 v236, v[122:123] offset:32
	ds_write_b64 v236, v[126:127] offset:48
	v_cvt_pk_bf16_f32 v98, v98, v99
	v_cvt_pk_bf16_f32 v99, v100, v101
	v_cvt_pk_bf16_f32 v102, v102, v103
	v_cvt_pk_bf16_f32 v103, v104, v105
	v_cvt_pk_bf16_f32 v106, v106, v107
	v_cvt_pk_bf16_f32 v107, v108, v109
	v_cvt_pk_bf16_f32 v110, v110, v111
	v_cvt_pk_bf16_f32 v111, v112, v113
	ds_write_b64 v236, v[98:99] offset:64
	ds_write_b64 v236, v[102:103] offset:80
	ds_write_b64 v236, v[106:107] offset:96
	ds_write_b64 v236, v[110:111] offset:112
	v_cvt_pk_bf16_f32 v82, v82, v83
	v_cvt_pk_bf16_f32 v83, v84, v85
	v_cvt_pk_bf16_f32 v86, v86, v87
	v_cvt_pk_bf16_f32 v87, v88, v89
	v_cvt_pk_bf16_f32 v90, v90, v91
	v_cvt_pk_bf16_f32 v91, v92, v93
	v_cvt_pk_bf16_f32 v94, v94, v95
	v_cvt_pk_bf16_f32 v95, v96, v97
	ds_write_b64 v236, v[82:83] offset:16640
	ds_write_b64 v236, v[86:87] offset:16656
	ds_write_b64 v236, v[90:91] offset:16672
	ds_write_b64 v236, v[94:95] offset:16688
	v_cvt_pk_bf16_f32 v66, v66, v67
	v_cvt_pk_bf16_f32 v67, v68, v69
	v_cvt_pk_bf16_f32 v70, v70, v71
	v_cvt_pk_bf16_f32 v71, v72, v73
	v_cvt_pk_bf16_f32 v74, v74, v75
	v_cvt_pk_bf16_f32 v75, v76, v77
	v_cvt_pk_bf16_f32 v78, v78, v79
	v_cvt_pk_bf16_f32 v79, v80, v81
	ds_write_b64 v236, v[66:67] offset:16704
	ds_write_b64 v236, v[70:71] offset:16720
	ds_write_b64 v236, v[74:75] offset:16736
	ds_write_b64 v236, v[78:79] offset:16752
	v_cvt_pk_bf16_f32 v50, v50, v51
	v_cvt_pk_bf16_f32 v51, v52, v53
	v_cvt_pk_bf16_f32 v54, v54, v55
	v_cvt_pk_bf16_f32 v55, v56, v57
	v_cvt_pk_bf16_f32 v58, v58, v59
	v_cvt_pk_bf16_f32 v59, v60, v61
	v_cvt_pk_bf16_f32 v62, v62, v63
	v_cvt_pk_bf16_f32 v63, v64, v65
	ds_write_b64 v236, v[50:51] offset:33280
	ds_write_b64 v236, v[54:55] offset:33296
	ds_write_b64 v236, v[58:59] offset:33312
	ds_write_b64 v236, v[62:63] offset:33328
	v_cvt_pk_bf16_f32 v34, v34, v35
	v_cvt_pk_bf16_f32 v35, v36, v37
	v_cvt_pk_bf16_f32 v38, v38, v39
	v_cvt_pk_bf16_f32 v39, v40, v41
	v_cvt_pk_bf16_f32 v42, v42, v43
	v_cvt_pk_bf16_f32 v43, v44, v45
	v_cvt_pk_bf16_f32 v46, v46, v47
	v_cvt_pk_bf16_f32 v47, v48, v49
	ds_write_b64 v236, v[34:35] offset:33344
	ds_write_b64 v236, v[38:39] offset:33360
	ds_write_b64 v236, v[42:43] offset:33376
	ds_write_b64 v236, v[46:47] offset:33392
	v_cvt_pk_bf16_f32 v18, v18, v19
	v_cvt_pk_bf16_f32 v19, v20, v21
	v_cvt_pk_bf16_f32 v22, v22, v23
	v_cvt_pk_bf16_f32 v23, v24, v25
	v_cvt_pk_bf16_f32 v26, v26, v27
	v_cvt_pk_bf16_f32 v27, v28, v29
	v_cvt_pk_bf16_f32 v30, v30, v31
	v_cvt_pk_bf16_f32 v31, v32, v33
	ds_write_b64 v236, v[18:19] offset:49920
	ds_write_b64 v236, v[22:23] offset:49936
	ds_write_b64 v236, v[26:27] offset:49952
	ds_write_b64 v236, v[30:31] offset:49968
	v_cvt_pk_bf16_f32 v2, v2, v3
	v_cvt_pk_bf16_f32 v3, v4, v5
	v_cvt_pk_bf16_f32 v6, v6, v7
	v_cvt_pk_bf16_f32 v7, v8, v9
	v_cvt_pk_bf16_f32 v10, v10, v11
	v_cvt_pk_bf16_f32 v11, v12, v13
	v_cvt_pk_bf16_f32 v14, v14, v15
	v_cvt_pk_bf16_f32 v15, v16, v17
	ds_write_b64 v236, v[2:3] offset:49984
	ds_write_b64 v236, v[6:7] offset:50000
	ds_write_b64 v236, v[10:11] offset:50016
	ds_write_b64 v236, v[14:15] offset:50032
	s_waitcnt lgkmcnt(0)
	s_barrier
	s_cmp_eq_u32 s10, 0
	s_cbranch_scc1 .Lg3_nok2_m0
	global_load_dwordx4 v[66:69], v206, s[98:99]
	global_load_dwordx4 v[70:73], v207, s[98:99]
	global_load_dwordx4 v[74:77], v208, s[98:99]
	global_load_dwordx4 v[78:81], v238, s[98:99]
	global_load_dwordx4 v[82:85], v206, s[100:101]
	global_load_dwordx4 v[86:89], v207, s[100:101]
	global_load_dwordx4 v[90:93], v208, s[100:101]
	global_load_dwordx4 v[94:97], v238, s[100:101]
; DI void gemm_phase(const Params& p, int layer, int mode, int nrows, char* lds_all) {
;     ...
;         for (int idx = tid; idx < 128 * 32; idx += 512) {
;           const int rr = idx >> 5, c8 = (idx & 31) * 8;
;           const int row = m0 + half * 128 + rr, col = n0 + c8;
;           const float4 v0 = *(const float4*)(Cs + rr * CSW + c8), v1 = *(const float4*)(Cs + rr * CSW + c8 + 4);
;           if (mode == 0) {
;             uint4 o;
;             o.x = pack2(v0.x, v0.y); o.y = pack2(v0.z, v0.w); o.z = pack2(v1.x, v1.y); o.w = pack2(v1.z, v1.w);
;             *(uint4*)((u16*)(p.ws + O_Z) + (size_t)row * ZW + col) = o;
.Lg3_nok2_m0:
	v_lshrrev_b32_e32 v237, 5, v165
	v_and_b32_e32 v194, 31, v165
	v_mul_u32_u24_e32 v235, 0x208, v237
	v_lshl_add_u32 v235, v194, 4, v235
	ds_read2_b64 v[2:5], v235 offset1:1
	v_add_u32_e32 v235, 0x2080, v235
	ds_read2_b64 v[6:9], v235 offset1:1
	v_add_u32_e32 v235, 0x2080, v235
	ds_read2_b64 v[10:13], v235 offset1:1
	v_add_u32_e32 v235, 0x2080, v235
	ds_read2_b64 v[14:17], v235 offset1:1
	v_add_u32_e32 v235, 0x2080, v235
	ds_read2_b64 v[18:21], v235 offset1:1
	v_add_u32_e32 v235, 0x2080, v235
	ds_read2_b64 v[22:25], v235 offset1:1
	v_add_u32_e32 v235, 0x2080, v235
	ds_read2_b64 v[26:29], v235 offset1:1
	v_add_u32_e32 v235, 0x2080, v235
	ds_read2_b64 v[30:33], v235 offset1:1
	v_add_u32_e32 v235, 0x2080, v235
	ds_read2_b64 v[34:37], v235 offset1:1
	v_add_u32_e32 v235, 0x2080, v235
	ds_read2_b64 v[38:41], v235 offset1:1
	v_add_u32_e32 v235, 0x2080, v235
	ds_read2_b64 v[42:45], v235 offset1:1
	v_add_u32_e32 v235, 0x2080, v235
	ds_read2_b64 v[46:49], v235 offset1:1
	v_add_u32_e32 v235, 0x2080, v235
	ds_read2_b64 v[50:53], v235 offset1:1
	v_add_u32_e32 v235, 0x2080, v235
	ds_read2_b64 v[54:57], v235 offset1:1
	v_add_u32_e32 v235, 0x2080, v235
	ds_read2_b64 v[58:61], v235 offset1:1
	v_add_u32_e32 v235, 0x2080, v235
	ds_read2_b64 v[62:65], v235 offset1:1
	s_waitcnt lgkmcnt(15)
	global_store_dwordx4 v234, v[2:5], s[50:51]
	v_add_u32_e32 v234, 0x16000, v234
	s_waitcnt lgkmcnt(14)
	global_store_dwordx4 v234, v[6:9], s[50:51]
	v_add_u32_e32 v234, 0x16000, v234
	s_waitcnt lgkmcnt(13)
	global_store_dwordx4 v234, v[10:13], s[50:51]
	v_add_u32_e32 v234, 0x16000, v234
	s_waitcnt lgkmcnt(12)
	global_store_dwordx4 v234, v[14:17], s[50:51]
	v_add_u32_e32 v234, 0x16000, v234
	s_waitcnt lgkmcnt(11)
	global_store_dwordx4 v234, v[18:21], s[50:51]
	v_add_u32_e32 v234, 0x16000, v234
	s_waitcnt lgkmcnt(10)
	global_store_dwordx4 v234, v[22:25], s[50:51]
	v_add_u32_e32 v234, 0x16000, v234
	s_waitcnt lgkmcnt(9)
	global_store_dwordx4 v234, v[26:29], s[50:51]
	v_add_u32_e32 v234, 0x16000, v234
	s_waitcnt lgkmcnt(8)
	global_store_dwordx4 v234, v[30:33], s[50:51]
	v_add_u32_e32 v234, 0x16000, v234
	s_waitcnt lgkmcnt(7)
	global_store_dwordx4 v234, v[34:37], s[50:51]
	v_add_u32_e32 v234, 0x16000, v234
	s_waitcnt lgkmcnt(6)
	global_store_dwordx4 v234, v[38:41], s[50:51]
	v_add_u32_e32 v234, 0x16000, v234
	s_waitcnt lgkmcnt(5)
	global_store_dwordx4 v234, v[42:45], s[50:51]
	v_add_u32_e32 v234, 0x16000, v234
	s_waitcnt lgkmcnt(4)
	global_store_dwordx4 v234, v[46:49], s[50:51]
	v_add_u32_e32 v234, 0x16000, v234
	s_waitcnt lgkmcnt(3)
	global_store_dwordx4 v234, v[50:53], s[50:51]
	v_add_u32_e32 v234, 0x16000, v234
	s_waitcnt lgkmcnt(2)
	global_store_dwordx4 v234, v[54:57], s[50:51]
	v_add_u32_e32 v234, 0x16000, v234
	s_waitcnt lgkmcnt(1)
	global_store_dwordx4 v234, v[58:61], s[50:51]
	v_add_u32_e32 v234, 0x16000, v234
	s_waitcnt lgkmcnt(0)
	global_store_dwordx4 v234, v[62:65], s[50:51]
	s_cmp_lg_u32 s10, 0
	s_cbranch_scc1 .Lg3_start_m0
	v_mov_b32_e32 v190, 0x10c20
	v_mov_b32_e32 v191, 0x11040
	v_mov_b32_e32 v192, 0x11460
	v_mov_b32_e32 v193, 0x12900
	v_mov_b32_e32 v194, 0x12d20
	v_mov_b32_e32 v195, 0x13140
	v_mov_b32_e32 v196, 0x13560
	v_mov_b32_e32 v197, 0x14a00
	v_mov_b32_e32 v198, 0x14e20
	v_mov_b32_e32 v199, 0x15240
	v_mov_b32_e32 v200, 0x15660
	v_mov_b32_e32 v201, 0x16b00
	v_mov_b32_e32 v202, 0x16f20
	v_mov_b32_e32 v203, 0x17340
	v_mov_b32_e32 v204, 0x17760
	v_mov_b32_e32 v205, 0x18c00
	v_mov_b32_e32 v206, 0x19020
	v_mov_b32_e32 v207, 0x19440
	v_mov_b32_e32 v208, 0x10800
	s_branch .LBB0_209

; #define G5_LOAD(k0)                                                                 \
;   {                                                                                 \
;     _Pragma("unroll") for (int i_ = 0; i_ < 4; ++i_) ra[i_] = ldg16(Ap + (size_t)(i_ * 64) * lda + (k0)); \
;     _Pragma("unroll") for (int i_ = 0; i_ < 4; ++i_) rb[i_] = ldg16(Bp + (size_t)(i_ * 64) * ldb + (k0)); \
;   }
; #define G5_STORE(s)                                                                 \
;   {                                                                                 \
;     _Pragma("unroll") for (int i_ = 0; i_ < 4; ++i_) *(u32x4*)(Sw + (s) * STG + i_ * 64 * GS) = ra[i_]; \
;     _Pragma("unroll") for (int i_ = 0; i_ < 4; ++i_) *(u32x4*)(Sw + (s) * STG + 256 * GS + i_ * 64 * GS) = rb[i_]; \
;   }
; template <typename Epi>
; DI void gemm_tile512(const u16* __restrict__ A, int lda, const u16* __restrict__ Bt, int ldb, int K, char* lds_all, Epi epi) {
;     ...
;   const int nk = K >> 6;
;   __syncthreads();
;   G5_LOAD(0);
;   G5_STORE(0);
;   G5_LOAD(64);
;   __syncthreads();
; DI void gemm_phase(const Params& p, int layer, int mode, int nrows, char* lds_all) {
;     ...
;   for (int i = jb;; i += nj) {
;     const int srl = i / per, rem = i - srl * per;
;     const int sr = xcd + nx * srl;
;     if (sr >= nsr) break;
;     const int tn = rem >> 1, tm = sr * 2 + (rem & 1);
;     const int m0 = tm * 256, n0 = tn * 256;
;     gemm_tile512(A + (size_t)m0 * lda, lda, Bt + (size_t)n0 * ldb, ldb, K, lds_all, [&](int half) {
.Lm2map_done_a:
	s_mul_i32 s4, s22, 0x900
	v_readlane_b32 s8, v250, 46
	s_mul_hi_i32 s5, s22, 0x900
	s_add_u32 s4, s8, s4
	v_readlane_b32 s8, v250, 47
	s_addc_u32 s5, s8, s5
	s_mul_i32 s8, s23, 0x900
	s_mul_hi_i32 s9, s23, 0x900
	s_add_u32 s8, s14, s8
	s_addc_u32 s9, s15, s9
	s_mov_b64 s[26:27], s[4:5]
	s_mov_b64 s[98:99], s[26:27]
	s_mov_b64 s[100:101], s[8:9]
	v_lshrrev_b32_e32 v239, 3, v165
	v_and_b32_e32 v0, 7, v165
	v_mul_u32_u24_e32 v206, 0x900, v239
	v_lshl_add_u32 v206, v0, 4, v206
	v_add_u32_e32 v207, 0x24000, v206
	v_add_u32_e32 v208, 0x48000, v206
	v_add_u32_e32 v238, 0x6c000, v206
	global_load_dwordx4 v[130:133], v206, s[98:99]
	global_load_dwordx4 v[134:137], v207, s[98:99]
	global_load_dwordx4 v[138:141], v208, s[98:99]
	global_load_dwordx4 v[142:145], v238, s[98:99]
	global_load_dwordx4 v[146:149], v206, s[100:101]
	global_load_dwordx4 v[150:153], v207, s[100:101]
	global_load_dwordx4 v[154:157], v208, s[100:101]
	global_load_dwordx4 v[158:161], v238, s[100:101]
	global_load_dwordx4 v[218:221], v206, s[98:99] offset:128
	global_load_dwordx4 v[222:225], v207, s[98:99] offset:128
	global_load_dwordx4 v[226:229], v208, s[98:99] offset:128
	global_load_dwordx4 v[230:233], v238, s[98:99] offset:128
	global_load_dwordx4 v[166:169], v206, s[100:101] offset:128
	global_load_dwordx4 v[170:173], v207, s[100:101] offset:128
	global_load_dwordx4 v[174:177], v208, s[100:101] offset:128
	global_load_dwordx4 v[190:193], v238, s[100:101] offset:128
	s_add_u32 s98, s98, 0x100
	s_addc_u32 s99, s99, 0
	s_add_u32 s100, s100, 0x100
	s_addc_u32 s101, s101, 0
	global_load_dwordx4 v[66:69], v206, s[98:99]
	global_load_dwordx4 v[70:73], v207, s[98:99]
	global_load_dwordx4 v[74:77], v208, s[98:99]
	global_load_dwordx4 v[78:81], v238, s[98:99]
	global_load_dwordx4 v[82:85], v206, s[100:101]
	global_load_dwordx4 v[86:89], v207, s[100:101]
	global_load_dwordx4 v[90:93], v208, s[100:101]
	global_load_dwordx4 v[94:97], v238, s[100:101]
	v_lshrrev_b32_e32 v239, 3, v165
	v_and_b32_e32 v0, 7, v165
	v_mul_u32_u24_e32 v180, 0x90, v239
	v_lshl_add_u32 v180, v0, 4, v180
	v_and_b32_e32 v239, 31, v165
	v_bfe_u32 v0, v165, 5, 1
	v_lshrrev_b32_e32 v179, 8, v165
	v_lshl_or_b32 v178, v179, 7, v239
	v_mul_u32_u24_e32 v178, 0x90, v178
	v_lshl_add_u32 v178, v0, 4, v178
	v_bfe_u32 v179, v165, 6, 2
	v_lshl_or_b32 v179, v179, 6, v239
	v_mul_u32_u24_e32 v179, 0x90, v179
	v_lshl_add_u32 v179, v0, 4, v179
	s_mov_b32 s11, 0x12000
	s_mov_b32 s12, 12
	s_barrier
	s_waitcnt vmcnt(23)
	ds_write_b128 v180, v[130:133]
	s_waitcnt vmcnt(22)
	ds_write_b128 v180, v[134:137] offset:9216
	s_waitcnt vmcnt(21)
	ds_write_b128 v180, v[138:141] offset:18432
	s_waitcnt vmcnt(20)
	ds_write_b128 v180, v[142:145] offset:27648
	s_waitcnt vmcnt(19)
	ds_write_b128 v180, v[146:149] offset:36864
	s_waitcnt vmcnt(18)
	ds_write_b128 v180, v[150:153] offset:46080
	s_waitcnt vmcnt(17)
	ds_write_b128 v180, v[154:157] offset:55296
	s_waitcnt vmcnt(16)
	ds_write_b128 v180, v[158:161] offset:64512
	v_add_u32_e32 v180, 0x12000, v180
	s_waitcnt vmcnt(15)
	ds_write_b128 v180, v[218:221]
	s_waitcnt vmcnt(14)
	ds_write_b128 v180, v[222:225] offset:9216
	s_waitcnt vmcnt(13)
	ds_write_b128 v180, v[226:229] offset:18432
	s_waitcnt vmcnt(12)
	ds_write_b128 v180, v[230:233] offset:27648
	s_waitcnt vmcnt(11)
	ds_write_b128 v180, v[166:169] offset:36864
	s_waitcnt vmcnt(10)
	ds_write_b128 v180, v[170:173] offset:46080
	s_waitcnt vmcnt(9)
	ds_write_b128 v180, v[174:177] offset:55296
	s_waitcnt vmcnt(8)
	ds_write_b128 v180, v[190:193] offset:64512
	s_waitcnt vmcnt(0)
	v_mov_b64_e32 v[130:131], v[66:67]
	v_mov_b64_e32 v[132:133], v[68:69]
	v_mov_b64_e32 v[134:135], v[70:71]
	v_mov_b64_e32 v[136:137], v[72:73]
	v_mov_b64_e32 v[138:139], v[74:75]
	v_mov_b64_e32 v[140:141], v[76:77]
	v_mov_b64_e32 v[142:143], v[78:79]
	v_mov_b64_e32 v[144:145], v[80:81]
	v_mov_b64_e32 v[146:147], v[82:83]
	v_mov_b64_e32 v[148:149], v[84:85]
	v_mov_b64_e32 v[150:151], v[86:87]
	v_mov_b64_e32 v[152:153], v[88:89]
	v_mov_b64_e32 v[154:155], v[90:91]
	v_mov_b64_e32 v[156:157], v[92:93]
	v_mov_b64_e32 v[158:159], v[94:95]
	v_mov_b64_e32 v[160:161], v[96:97]
	s_waitcnt lgkmcnt(0)
	s_branch .Lg3_k_m2
.Lg3_start_m2:
	v_lshrrev_b32_e32 v239, 3, v165
	v_and_b32_e32 v0, 7, v165
	v_mul_u32_u24_e32 v180, 0x90, v239
	v_lshl_add_u32 v180, v0, 4, v180
	v_and_b32_e32 v239, 31, v165
	v_bfe_u32 v0, v165, 5, 1
	v_lshrrev_b32_e32 v179, 8, v165
	v_lshl_or_b32 v178, v179, 7, v239
	v_mul_u32_u24_e32 v178, 0x90, v178
	v_lshl_add_u32 v178, v0, 4, v178
	v_bfe_u32 v179, v165, 6, 2
	v_lshl_or_b32 v179, v179, 6, v239
	v_mul_u32_u24_e32 v179, 0x90, v179
	v_lshl_add_u32 v179, v0, 4, v179
	s_mov_b32 s11, 0x12000
	s_mov_b32 s12, 12
	s_barrier
	s_waitcnt vmcnt(39)
	ds_write_b128 v180, v[130:133]
	s_waitcnt vmcnt(38)
	ds_write_b128 v180, v[134:137] offset:9216
	s_waitcnt vmcnt(37)
	ds_write_b128 v180, v[138:141] offset:18432
	s_waitcnt vmcnt(36)
	ds_write_b128 v180, v[142:145] offset:27648
	s_waitcnt vmcnt(35)
	ds_write_b128 v180, v[146:149] offset:36864
	s_waitcnt vmcnt(34)
	ds_write_b128 v180, v[150:153] offset:46080
	s_waitcnt vmcnt(33)
	ds_write_b128 v180, v[154:157] offset:55296
	s_waitcnt vmcnt(32)
	ds_write_b128 v180, v[158:161] offset:64512
	v_add_u32_e32 v180, 0x12000, v180
	s_waitcnt vmcnt(31)
	ds_write_b128 v180, v[218:221]
	s_waitcnt vmcnt(30)
	ds_write_b128 v180, v[222:225] offset:9216
	s_waitcnt vmcnt(29)
	ds_write_b128 v180, v[226:229] offset:18432
	s_waitcnt vmcnt(28)
	ds_write_b128 v180, v[230:233] offset:27648
	s_waitcnt vmcnt(27)
	ds_write_b128 v180, v[166:169] offset:36864
	s_waitcnt vmcnt(26)
	ds_write_b128 v180, v[170:173] offset:46080
	s_waitcnt vmcnt(25)
	ds_write_b128 v180, v[174:177] offset:55296
	s_waitcnt vmcnt(24)
	ds_write_b128 v180, v[190:193] offset:64512
	s_waitcnt vmcnt(16)
	v_mov_b64_e32 v[130:131], v[66:67]
	v_mov_b64_e32 v[132:133], v[68:69]
	v_mov_b64_e32 v[134:135], v[70:71]
	v_mov_b64_e32 v[136:137], v[72:73]
	v_mov_b64_e32 v[138:139], v[74:75]
	v_mov_b64_e32 v[140:141], v[76:77]
	v_mov_b64_e32 v[142:143], v[78:79]
	v_mov_b64_e32 v[144:145], v[80:81]
	v_mov_b64_e32 v[146:147], v[82:83]
	v_mov_b64_e32 v[148:149], v[84:85]
	v_mov_b64_e32 v[150:151], v[86:87]
	v_mov_b64_e32 v[152:153], v[88:89]
	v_mov_b64_e32 v[154:155], v[90:91]
	v_mov_b64_e32 v[156:157], v[92:93]
	v_mov_b64_e32 v[158:159], v[94:95]
	v_mov_b64_e32 v[160:161], v[96:97]
	s_waitcnt lgkmcnt(0)
; #define G5_LOAD(k0)                                                                 \
;   {                                                                                 \
;     _Pragma("unroll") for (int i_ = 0; i_ < 4; ++i_) ra[i_] = ldg16(Ap + (size_t)(i_ * 64) * lda + (k0)); \
;     _Pragma("unroll") for (int i_ = 0; i_ < 4; ++i_) rb[i_] = ldg16(Bp + (size_t)(i_ * 64) * ldb + (k0)); \
;   }
; #define G5_STORE(s)                                                                 \
;   {                                                                                 \
;     _Pragma("unroll") for (int i_ = 0; i_ < 4; ++i_) *(u32x4*)(Sw + (s) * STG + i_ * 64 * GS) = ra[i_]; \
;     _Pragma("unroll") for (int i_ = 0; i_ < 4; ++i_) *(u32x4*)(Sw + (s) * STG + 256 * GS + i_ * 64 * GS) = rb[i_]; \
;   }
; template <typename Epi>
; DI void gemm_tile512(const u16* __restrict__ A, int lda, const u16* __restrict__ Bt, int ldb, int K, char* lds_all, Epi epi) {
;     ...
;   for (int kt = 0; kt + 2 < nk; ++kt) {
;     const int cur = kt & 1;
;     G5_COMPUTE(cur);
;     G5_STORE(cur ^ 1);
;     G5_LOAD((kt + 2) << 6);
;     __syncthreads();
;   }
.Lg3_k_m2:
	s_barrier
	ds_read_b128 v[194:197], v179 offset:36864
	ds_read_b128 v[166:169], v178
	ds_read_b128 v[198:201], v179 offset:41472
	ds_read_b128 v[170:173], v178 offset:4608
	ds_read_b128 v[174:177], v178 offset:9216
	ds_read_b128 v[190:193], v178 offset:13824
	s_waitcnt lgkmcnt(4)
	v_mfma_f32_32x32x16_bf16 v[114:129], v[194:197], v[166:169], 0
	ds_read_b128 v[234:237], v179 offset:36896
	s_waitcnt lgkmcnt(4)
	v_mfma_f32_32x32x16_bf16 v[98:113], v[198:201], v[166:169], 0
	ds_read_b128 v[218:221], v178 offset:32
	s_waitcnt lgkmcnt(4)
	v_mfma_f32_32x32x16_bf16 v[82:97], v[194:197], v[170:173], 0
	ds_read_b128 v[202:205], v179 offset:41504
	v_mfma_f32_32x32x16_bf16 v[66:81], v[198:201], v[170:173], 0
	ds_read_b128 v[222:225], v178 offset:4640
	s_waitcnt lgkmcnt(5)
	v_mfma_f32_32x32x16_bf16 v[50:65], v[194:197], v[174:177], 0
	ds_read_b128 v[226:229], v178 offset:9248
	v_mfma_f32_32x32x16_bf16 v[34:49], v[198:201], v[174:177], 0
	ds_read_b128 v[230:233], v178 offset:13856
	s_waitcnt lgkmcnt(6)
	v_mfma_f32_32x32x16_bf16 v[18:33], v[194:197], v[190:193], 0
	v_mfma_f32_32x32x16_bf16 v[2:17], v[198:201], v[190:193], 0
	s_waitcnt lgkmcnt(4)
	v_mfma_f32_32x32x16_bf16 v[114:129], v[234:237], v[218:221], v[114:129]
	ds_read_b128 v[194:197], v179 offset:36928
	s_waitcnt lgkmcnt(4)
	v_mfma_f32_32x32x16_bf16 v[98:113], v[202:205], v[218:221], v[98:113]
	ds_read_b128 v[166:169], v178 offset:64
	s_waitcnt lgkmcnt(4)
	v_mfma_f32_32x32x16_bf16 v[82:97], v[234:237], v[222:225], v[82:97]
	ds_read_b128 v[198:201], v179 offset:41536
	v_mfma_f32_32x32x16_bf16 v[66:81], v[202:205], v[222:225], v[66:81]
	ds_read_b128 v[170:173], v178 offset:4672
	s_waitcnt lgkmcnt(5)
	v_mfma_f32_32x32x16_bf16 v[50:65], v[234:237], v[226:229], v[50:65]
	ds_read_b128 v[174:177], v178 offset:9280
	v_mfma_f32_32x32x16_bf16 v[34:49], v[202:205], v[226:229], v[34:49]
	ds_read_b128 v[190:193], v178 offset:13888
	s_waitcnt lgkmcnt(6)
	v_mfma_f32_32x32x16_bf16 v[18:33], v[234:237], v[230:233], v[18:33]
	v_mfma_f32_32x32x16_bf16 v[2:17], v[202:205], v[230:233], v[2:17]
	v_subrev_u32_e32 v180, s11, v180
	s_waitcnt lgkmcnt(4)
	v_mfma_f32_32x32x16_bf16 v[114:129], v[194:197], v[166:169], v[114:129]
	ds_read_b128 v[234:237], v179 offset:36960
	s_waitcnt lgkmcnt(4)
	v_mfma_f32_32x32x16_bf16 v[98:113], v[198:201], v[166:169], v[98:113]
	ds_read_b128 v[218:221], v178 offset:96
	s_waitcnt lgkmcnt(4)
	v_mfma_f32_32x32x16_bf16 v[82:97], v[194:197], v[170:173], v[82:97]
	ds_read_b128 v[202:205], v179 offset:41568
	v_mfma_f32_32x32x16_bf16 v[66:81], v[198:201], v[170:173], v[66:81]
	ds_read_b128 v[222:225], v178 offset:4704
	s_waitcnt lgkmcnt(5)
	v_mfma_f32_32x32x16_bf16 v[50:65], v[194:197], v[174:177], v[50:65]
	ds_read_b128 v[226:229], v178 offset:9312
	v_mfma_f32_32x32x16_bf16 v[34:49], v[198:201], v[174:177], v[34:49]
	ds_read_b128 v[230:233], v178 offset:13920
	v_add_u32_e32 v178, s11, v178
	v_add_u32_e32 v179, s11, v179
	s_waitcnt lgkmcnt(6)
	v_mfma_f32_32x32x16_bf16 v[18:33], v[194:197], v[190:193], v[18:33]
	v_mfma_f32_32x32x16_bf16 v[2:17], v[198:201], v[190:193], v[2:17]
	s_sub_u32 s11, 0, s11
	s_add_u32 s98, s98, 0x80
	s_addc_u32 s99, s99, 0
	s_add_u32 s100, s100, 0x80
	s_addc_u32 s101, s101, 0
	s_waitcnt lgkmcnt(0)
	s_barrier
; #define G5_LOAD(k0)                                                                 \
;   {                                                                                 \
;     _Pragma("unroll") for (int i_ = 0; i_ < 4; ++i_) ra[i_] = ldg16(Ap + (size_t)(i_ * 64) * lda + (k0)); \
;     _Pragma("unroll") for (int i_ = 0; i_ < 4; ++i_) rb[i_] = ldg16(Bp + (size_t)(i_ * 64) * ldb + (k0)); \
;   }
; #define G5_STORE(s)                                                                 \
;   {                                                                                 \
;     _Pragma("unroll") for (int i_ = 0; i_ < 4; ++i_) *(u32x4*)(Sw + (s) * STG + i_ * 64 * GS) = ra[i_]; \
;     _Pragma("unroll") for (int i_ = 0; i_ < 4; ++i_) *(u32x4*)(Sw + (s) * STG + 256 * GS + i_ * 64 * GS) = rb[i_]; \
;   }
; template <typename Epi>
; DI void gemm_tile512(const u16* __restrict__ A, int lda, const u16* __restrict__ Bt, int ldb, int K, char* lds_all, Epi epi) {
;     ...
;   for (int kt = 0; kt + 2 < nk; ++kt) {
;     const int cur = kt & 1;
;     G5_COMPUTE(cur);
;     G5_STORE(cur ^ 1);
;     G5_LOAD((kt + 2) << 6);
;     __syncthreads();
;   }
	ds_read_b128 v[194:197], v179 offset:36864
	ds_read_b128 v[166:169], v178
	v_mfma_f32_32x32x16_bf16 v[114:129], v[234:237], v[218:221], v[114:129]
	ds_read_b128 v[198:201], v179 offset:41472
	v_mfma_f32_32x32x16_bf16 v[98:113], v[202:205], v[218:221], v[98:113]
	ds_read_b128 v[170:173], v178 offset:4608
	v_mfma_f32_32x32x16_bf16 v[82:97], v[234:237], v[222:225], v[82:97]
	ds_read_b128 v[174:177], v178 offset:9216
	v_mfma_f32_32x32x16_bf16 v[66:81], v[202:205], v[222:225], v[66:81]
	ds_read_b128 v[190:193], v178 offset:13824
	v_mfma_f32_32x32x16_bf16 v[50:65], v[234:237], v[226:229], v[50:65]
	v_mfma_f32_32x32x16_bf16 v[34:49], v[202:205], v[226:229], v[34:49]
	v_mfma_f32_32x32x16_bf16 v[18:33], v[234:237], v[230:233], v[18:33]
	v_mfma_f32_32x32x16_bf16 v[2:17], v[202:205], v[230:233], v[2:17]
	s_waitcnt lgkmcnt(4)
	v_mfma_f32_32x32x16_bf16 v[114:129], v[194:197], v[166:169], v[114:129]
	ds_read_b128 v[234:237], v179 offset:36896
	s_waitcnt lgkmcnt(4)
	v_mfma_f32_32x32x16_bf16 v[98:113], v[198:201], v[166:169], v[98:113]
	ds_read_b128 v[218:221], v178 offset:32
	ds_write_b128 v180, v[130:133]
	global_load_dwordx4 v[130:133], v206, s[98:99]
	s_waitcnt lgkmcnt(5)
	v_mfma_f32_32x32x16_bf16 v[82:97], v[194:197], v[170:173], v[82:97]
	ds_read_b128 v[202:205], v179 offset:41504
	v_mfma_f32_32x32x16_bf16 v[66:81], v[198:201], v[170:173], v[66:81]
	ds_read_b128 v[222:225], v178 offset:4640
	ds_write_b128 v180, v[134:137] offset:9216
	global_load_dwordx4 v[134:137], v207, s[98:99]
	s_waitcnt lgkmcnt(7)
	v_mfma_f32_32x32x16_bf16 v[50:65], v[194:197], v[174:177], v[50:65]
	ds_read_b128 v[226:229], v178 offset:9248
	v_mfma_f32_32x32x16_bf16 v[34:49], v[198:201], v[174:177], v[34:49]
	ds_read_b128 v[230:233], v178 offset:13856
	ds_write_b128 v180, v[138:141] offset:18432
	global_load_dwordx4 v[138:141], v208, s[98:99]
	s_waitcnt lgkmcnt(9)
	v_mfma_f32_32x32x16_bf16 v[18:33], v[194:197], v[190:193], v[18:33]
	v_mfma_f32_32x32x16_bf16 v[2:17], v[198:201], v[190:193], v[2:17]
	ds_write_b128 v180, v[142:145] offset:27648
	global_load_dwordx4 v[142:145], v238, s[98:99]
	s_waitcnt lgkmcnt(8)
	v_mfma_f32_32x32x16_bf16 v[114:129], v[234:237], v[218:221], v[114:129]
	ds_read_b128 v[194:197], v179 offset:36928
	s_waitcnt lgkmcnt(7)
	v_mfma_f32_32x32x16_bf16 v[98:113], v[202:205], v[218:221], v[98:113]
	ds_read_b128 v[166:169], v178 offset:64
	ds_write_b128 v180, v[146:149] offset:36864
	global_load_dwordx4 v[146:149], v206, s[100:101]
	s_waitcnt lgkmcnt(8)
	v_mfma_f32_32x32x16_bf16 v[82:97], v[234:237], v[222:225], v[82:97]
	ds_read_b128 v[198:201], v179 offset:41536
	v_mfma_f32_32x32x16_bf16 v[66:81], v[202:205], v[222:225], v[66:81]
	ds_read_b128 v[170:173], v178 offset:4672
	ds_write_b128 v180, v[150:153] offset:46080
	global_load_dwordx4 v[150:153], v207, s[100:101]
	s_waitcnt lgkmcnt(9)
	v_mfma_f32_32x32x16_bf16 v[50:65], v[234:237], v[226:229], v[50:65]
	ds_read_b128 v[174:177], v178 offset:9280
	v_mfma_f32_32x32x16_bf16 v[34:49], v[202:205], v[226:229], v[34:49]
	ds_read_b128 v[190:193], v178 offset:13888
	ds_write_b128 v180, v[154:157] offset:55296
	global_load_dwordx4 v[154:157], v208, s[100:101]
	s_waitcnt lgkmcnt(11)
	v_mfma_f32_32x32x16_bf16 v[18:33], v[234:237], v[230:233], v[18:33]
	v_mfma_f32_32x32x16_bf16 v[2:17], v[202:205], v[230:233], v[2:17]
	ds_write_b128 v180, v[158:161] offset:64512
	global_load_dwordx4 v[158:161], v238, s[100:101]
	v_subrev_u32_e32 v180, s11, v180
	s_waitcnt lgkmcnt(8)
	v_mfma_f32_32x32x16_bf16 v[114:129], v[194:197], v[166:169], v[114:129]
	ds_read_b128 v[234:237], v179 offset:36960
	s_waitcnt lgkmcnt(7)
	v_mfma_f32_32x32x16_bf16 v[98:113], v[198:201], v[166:169], v[98:113]
	ds_read_b128 v[218:221], v178 offset:96
	s_waitcnt lgkmcnt(7)
	v_mfma_f32_32x32x16_bf16 v[82:97], v[194:197], v[170:173], v[82:97]
	ds_read_b128 v[202:205], v179 offset:41568
	v_mfma_f32_32x32x16_bf16 v[66:81], v[198:201], v[170:173], v[66:81]
	ds_read_b128 v[222:225], v178 offset:4704
	s_waitcnt lgkmcnt(7)
	v_mfma_f32_32x32x16_bf16 v[50:65], v[194:197], v[174:177], v[50:65]
	ds_read_b128 v[226:229], v178 offset:9312
	v_mfma_f32_32x32x16_bf16 v[34:49], v[198:201], v[174:177], v[34:49]
	ds_read_b128 v[230:233], v178 offset:13920
	v_add_u32_e32 v178, s11, v178
	v_add_u32_e32 v179, s11, v179
	s_waitcnt lgkmcnt(8)
	v_mfma_f32_32x32x16_bf16 v[18:33], v[194:197], v[190:193], v[18:33]
	v_mfma_f32_32x32x16_bf16 v[2:17], v[198:201], v[190:193], v[2:17]
	s_sub_u32 s11, 0, s11
	s_add_u32 s98, s98, 0x80
	s_addc_u32 s99, s99, 0
	s_add_u32 s100, s100, 0x80
	s_addc_u32 s101, s101, 0
	s_waitcnt lgkmcnt(0)

; DI int crow(int reg, int h) { return (reg & 3) + 8 * (reg >> 2) + 4 * h; }
; template <typename Epi>
; DI void gemm_tile512(const u16* __restrict__ A, int lda, const u16* __restrict__ Bt, int ldb, int K, char* lds_all, Epi epi) {
;     ...
; #pragma unroll 1
;   for (int half = 0; half < 2; ++half) {
;     __syncthreads();
;     if (wm == half) {
; #pragma unroll
;       for (int i = 0; i < 4; ++i)
; #pragma unroll
;         for (int j = 0; j < 2; ++j)
; #pragma unroll
;           for (int g = 0; g < 16; ++g) Cs[(i * 32 + crow(g, h)) * CSW + wn * 64 + j * 32 + r] = acc[i][j][g];
;     }
;     __syncthreads();
;     epi(half);
;   }
; DI void gemm_phase(const Params& p, int layer, int mode, int nrows, char* lds_all) {
;     ...
;             const float a0 = fmaxf(v0.x, 0.f), a1 = fmaxf(v0.y, 0.f), a2 = fmaxf(v0.z, 0.f), a3 = fmaxf(v0.w, 0.f);
;             const float a4 = fmaxf(v1.x, 0.f), a5 = fmaxf(v1.y, 0.f), a6 = fmaxf(v1.z, 0.f), a7 = fmaxf(v1.w, 0.f);
;             uint4 o;
;             o.x = pack2(a0 * a0, a1 * a1); o.y = pack2(a2 * a2, a3 * a3); o.z = pack2(a4 * a4, a5 * a5); o.w = pack2(a6 * a6, a7 * a7);
;             *(uint4*)((u16*)(p.ws + O_Z) + (size_t)row * HP + col) = o;
.Lg3_nonext_m2:
	v_lshrrev_b32_e32 v237, 8, v165
	v_and_b32_e32 v194, 31, v165
	v_lshl_or_b32 v237, v237, 7, v194
	v_mul_u32_u24_e32 v236, 0x208, v237
	v_bfe_u32 v237, v165, 6, 2
	v_bfe_u32 v194, v165, 5, 1
	v_lshlrev_b32_e32 v237, 7, v237
	v_lshl_or_b32 v237, v194, 3, v237
	v_add_u32_e32 v236, v236, v237
	v_max_f32_e32 v114, 0, v114
	v_max_f32_e32 v115, 0, v115
	v_max_f32_e32 v116, 0, v116
	v_max_f32_e32 v117, 0, v117
	v_pk_mul_f32 v[114:115], v[114:115], v[114:115]
	v_pk_mul_f32 v[116:117], v[116:117], v[116:117]
	v_cvt_pk_bf16_f32 v114, v114, v115
	v_cvt_pk_bf16_f32 v115, v116, v117
	v_max_f32_e32 v118, 0, v118
	v_max_f32_e32 v119, 0, v119
	v_max_f32_e32 v120, 0, v120
	v_max_f32_e32 v121, 0, v121
	v_pk_mul_f32 v[118:119], v[118:119], v[118:119]
	v_pk_mul_f32 v[120:121], v[120:121], v[120:121]
	v_cvt_pk_bf16_f32 v118, v118, v119
	v_cvt_pk_bf16_f32 v119, v120, v121
	v_max_f32_e32 v122, 0, v122
	v_max_f32_e32 v123, 0, v123
	v_max_f32_e32 v124, 0, v124
	v_max_f32_e32 v125, 0, v125
	v_pk_mul_f32 v[122:123], v[122:123], v[122:123]
	v_pk_mul_f32 v[124:125], v[124:125], v[124:125]
	v_cvt_pk_bf16_f32 v122, v122, v123
	v_cvt_pk_bf16_f32 v123, v124, v125
	v_max_f32_e32 v126, 0, v126
	v_max_f32_e32 v127, 0, v127
	v_max_f32_e32 v128, 0, v128
	v_max_f32_e32 v129, 0, v129
	v_pk_mul_f32 v[126:127], v[126:127], v[126:127]
	v_pk_mul_f32 v[128:129], v[128:129], v[128:129]
	v_cvt_pk_bf16_f32 v126, v126, v127
	v_cvt_pk_bf16_f32 v127, v128, v129
	s_barrier
	ds_write_b64 v236, v[114:115]
	ds_write_b64 v236, v[118:119] offset:16
	ds_write_b64 v236, v[122:123] offset:32
	ds_write_b64 v236, v[126:127] offset:48
	v_max_f32_e32 v98, 0, v98
	v_max_f32_e32 v99, 0, v99
	v_max_f32_e32 v100, 0, v100
	v_max_f32_e32 v101, 0, v101
	v_pk_mul_f32 v[98:99], v[98:99], v[98:99]
	v_pk_mul_f32 v[100:101], v[100:101], v[100:101]
	v_cvt_pk_bf16_f32 v98, v98, v99
	v_cvt_pk_bf16_f32 v99, v100, v101
	v_max_f32_e32 v102, 0, v102
	v_max_f32_e32 v103, 0, v103
	v_max_f32_e32 v104, 0, v104
	v_max_f32_e32 v105, 0, v105
	v_pk_mul_f32 v[102:103], v[102:103], v[102:103]
	v_pk_mul_f32 v[104:105], v[104:105], v[104:105]
	v_cvt_pk_bf16_f32 v102, v102, v103
	v_cvt_pk_bf16_f32 v103, v104, v105
	v_max_f32_e32 v106, 0, v106
	v_max_f32_e32 v107, 0, v107
	v_max_f32_e32 v108, 0, v108
	v_max_f32_e32 v109, 0, v109
	v_pk_mul_f32 v[106:107], v[106:107], v[106:107]
	v_pk_mul_f32 v[108:109], v[108:109], v[108:109]
	v_cvt_pk_bf16_f32 v106, v106, v107
	v_cvt_pk_bf16_f32 v107, v108, v109
	v_max_f32_e32 v110, 0, v110
	v_max_f32_e32 v111, 0, v111
	v_max_f32_e32 v112, 0, v112
	v_max_f32_e32 v113, 0, v113
	v_pk_mul_f32 v[110:111], v[110:111], v[110:111]
	v_pk_mul_f32 v[112:113], v[112:113], v[112:113]
	v_cvt_pk_bf16_f32 v110, v110, v111
	v_cvt_pk_bf16_f32 v111, v112, v113
	ds_write_b64 v236, v[98:99] offset:64
	ds_write_b64 v236, v[102:103] offset:80
	ds_write_b64 v236, v[106:107] offset:96
	ds_write_b64 v236, v[110:111] offset:112
	v_max_f32_e32 v82, 0, v82
	v_max_f32_e32 v83, 0, v83
	v_max_f32_e32 v84, 0, v84
	v_max_f32_e32 v85, 0, v85
	v_pk_mul_f32 v[82:83], v[82:83], v[82:83]
	v_pk_mul_f32 v[84:85], v[84:85], v[84:85]
	v_cvt_pk_bf16_f32 v82, v82, v83
	v_cvt_pk_bf16_f32 v83, v84, v85
	v_max_f32_e32 v86, 0, v86
	v_max_f32_e32 v87, 0, v87
	v_max_f32_e32 v88, 0, v88
	v_max_f32_e32 v89, 0, v89
	v_pk_mul_f32 v[86:87], v[86:87], v[86:87]
	v_pk_mul_f32 v[88:89], v[88:89], v[88:89]
	v_cvt_pk_bf16_f32 v86, v86, v87
	v_cvt_pk_bf16_f32 v87, v88, v89
	v_max_f32_e32 v90, 0, v90
	v_max_f32_e32 v91, 0, v91
	v_max_f32_e32 v92, 0, v92
	v_max_f32_e32 v93, 0, v93
	v_pk_mul_f32 v[90:91], v[90:91], v[90:91]
	v_pk_mul_f32 v[92:93], v[92:93], v[92:93]
	v_cvt_pk_bf16_f32 v90, v90, v91
	v_cvt_pk_bf16_f32 v91, v92, v93
	v_max_f32_e32 v94, 0, v94
	v_max_f32_e32 v95, 0, v95
	v_max_f32_e32 v96, 0, v96
	v_max_f32_e32 v97, 0, v97
	v_pk_mul_f32 v[94:95], v[94:95], v[94:95]
	v_pk_mul_f32 v[96:97], v[96:97], v[96:97]
	v_cvt_pk_bf16_f32 v94, v94, v95
	v_cvt_pk_bf16_f32 v95, v96, v97
	ds_write_b64 v236, v[82:83] offset:16640
	ds_write_b64 v236, v[86:87] offset:16656
	ds_write_b64 v236, v[90:91] offset:16672
	ds_write_b64 v236, v[94:95] offset:16688
	v_max_f32_e32 v66, 0, v66
	v_max_f32_e32 v67, 0, v67
	v_max_f32_e32 v68, 0, v68
	v_max_f32_e32 v69, 0, v69
	v_pk_mul_f32 v[66:67], v[66:67], v[66:67]
	v_pk_mul_f32 v[68:69], v[68:69], v[68:69]
	v_cvt_pk_bf16_f32 v66, v66, v67
	v_cvt_pk_bf16_f32 v67, v68, v69
	v_max_f32_e32 v70, 0, v70
	v_max_f32_e32 v71, 0, v71
	v_max_f32_e32 v72, 0, v72
	v_max_f32_e32 v73, 0, v73
	v_pk_mul_f32 v[70:71], v[70:71], v[70:71]
	v_pk_mul_f32 v[72:73], v[72:73], v[72:73]
	v_cvt_pk_bf16_f32 v70, v70, v71
	v_cvt_pk_bf16_f32 v71, v72, v73
	v_max_f32_e32 v74, 0, v74
	v_max_f32_e32 v75, 0, v75
	v_max_f32_e32 v76, 0, v76
	v_max_f32_e32 v77, 0, v77
	v_pk_mul_f32 v[74:75], v[74:75], v[74:75]
	v_pk_mul_f32 v[76:77], v[76:77], v[76:77]
	v_cvt_pk_bf16_f32 v74, v74, v75
	v_cvt_pk_bf16_f32 v75, v76, v77
	v_max_f32_e32 v78, 0, v78
	v_max_f32_e32 v79, 0, v79
	v_max_f32_e32 v80, 0, v80
	v_max_f32_e32 v81, 0, v81
	v_pk_mul_f32 v[78:79], v[78:79], v[78:79]
	v_pk_mul_f32 v[80:81], v[80:81], v[80:81]
	v_cvt_pk_bf16_f32 v78, v78, v79
	v_cvt_pk_bf16_f32 v79, v80, v81
	ds_write_b64 v236, v[66:67] offset:16704
	ds_write_b64 v236, v[70:71] offset:16720
	ds_write_b64 v236, v[74:75] offset:16736
	ds_write_b64 v236, v[78:79] offset:16752
	v_max_f32_e32 v50, 0, v50
	v_max_f32_e32 v51, 0, v51
	v_max_f32_e32 v52, 0, v52
	v_max_f32_e32 v53, 0, v53
	v_pk_mul_f32 v[50:51], v[50:51], v[50:51]
	v_pk_mul_f32 v[52:53], v[52:53], v[52:53]
	v_cvt_pk_bf16_f32 v50, v50, v51
	v_cvt_pk_bf16_f32 v51, v52, v53
	v_max_f32_e32 v54, 0, v54
	v_max_f32_e32 v55, 0, v55
; DI int crow(int reg, int h) { return (reg & 3) + 8 * (reg >> 2) + 4 * h; }
; template <typename Epi>
; DI void gemm_tile512(const u16* __restrict__ A, int lda, const u16* __restrict__ Bt, int ldb, int K, char* lds_all, Epi epi) {
;     ...
; #pragma unroll 1
;   for (int half = 0; half < 2; ++half) {
;     __syncthreads();
;     if (wm == half) {
; #pragma unroll
;       for (int i = 0; i < 4; ++i)
; #pragma unroll
;         for (int j = 0; j < 2; ++j)
; #pragma unroll
;           for (int g = 0; g < 16; ++g) Cs[(i * 32 + crow(g, h)) * CSW + wn * 64 + j * 32 + r] = acc[i][j][g];
;     }
;     __syncthreads();
;     epi(half);
;   }
; DI void gemm_phase(const Params& p, int layer, int mode, int nrows, char* lds_all) {
;     ...
;             const float a0 = fmaxf(v0.x, 0.f), a1 = fmaxf(v0.y, 0.f), a2 = fmaxf(v0.z, 0.f), a3 = fmaxf(v0.w, 0.f);
;             const float a4 = fmaxf(v1.x, 0.f), a5 = fmaxf(v1.y, 0.f), a6 = fmaxf(v1.z, 0.f), a7 = fmaxf(v1.w, 0.f);
;             uint4 o;
;             o.x = pack2(a0 * a0, a1 * a1); o.y = pack2(a2 * a2, a3 * a3); o.z = pack2(a4 * a4, a5 * a5); o.w = pack2(a6 * a6, a7 * a7);
;             *(uint4*)((u16*)(p.ws + O_Z) + (size_t)row * HP + col) = o;
	v_max_f32_e32 v56, 0, v56
	v_max_f32_e32 v57, 0, v57
	v_pk_mul_f32 v[54:55], v[54:55], v[54:55]
	v_pk_mul_f32 v[56:57], v[56:57], v[56:57]
	v_cvt_pk_bf16_f32 v54, v54, v55
	v_cvt_pk_bf16_f32 v55, v56, v57
	v_max_f32_e32 v58, 0, v58
	v_max_f32_e32 v59, 0, v59
	v_max_f32_e32 v60, 0, v60
	v_max_f32_e32 v61, 0, v61
	v_pk_mul_f32 v[58:59], v[58:59], v[58:59]
	v_pk_mul_f32 v[60:61], v[60:61], v[60:61]
	v_cvt_pk_bf16_f32 v58, v58, v59
	v_cvt_pk_bf16_f32 v59, v60, v61
	v_max_f32_e32 v62, 0, v62
	v_max_f32_e32 v63, 0, v63
	v_max_f32_e32 v64, 0, v64
	v_max_f32_e32 v65, 0, v65
	v_pk_mul_f32 v[62:63], v[62:63], v[62:63]
	v_pk_mul_f32 v[64:65], v[64:65], v[64:65]
	v_cvt_pk_bf16_f32 v62, v62, v63
	v_cvt_pk_bf16_f32 v63, v64, v65
	ds_write_b64 v236, v[50:51] offset:33280
	ds_write_b64 v236, v[54:55] offset:33296
	ds_write_b64 v236, v[58:59] offset:33312
	ds_write_b64 v236, v[62:63] offset:33328
	v_max_f32_e32 v34, 0, v34
	v_max_f32_e32 v35, 0, v35
	v_max_f32_e32 v36, 0, v36
	v_max_f32_e32 v37, 0, v37
	v_pk_mul_f32 v[34:35], v[34:35], v[34:35]
	v_pk_mul_f32 v[36:37], v[36:37], v[36:37]
	v_cvt_pk_bf16_f32 v34, v34, v35
	v_cvt_pk_bf16_f32 v35, v36, v37
	v_max_f32_e32 v38, 0, v38
	v_max_f32_e32 v39, 0, v39
	v_max_f32_e32 v40, 0, v40
	v_max_f32_e32 v41, 0, v41
	v_pk_mul_f32 v[38:39], v[38:39], v[38:39]
	v_pk_mul_f32 v[40:41], v[40:41], v[40:41]
	v_cvt_pk_bf16_f32 v38, v38, v39
	v_cvt_pk_bf16_f32 v39, v40, v41
	v_max_f32_e32 v42, 0, v42
	v_max_f32_e32 v43, 0, v43
	v_max_f32_e32 v44, 0, v44
	v_max_f32_e32 v45, 0, v45
	v_pk_mul_f32 v[42:43], v[42:43], v[42:43]
	v_pk_mul_f32 v[44:45], v[44:45], v[44:45]
	v_cvt_pk_bf16_f32 v42, v42, v43
	v_cvt_pk_bf16_f32 v43, v44, v45
	v_max_f32_e32 v46, 0, v46
	v_max_f32_e32 v47, 0, v47
	v_max_f32_e32 v48, 0, v48
	v_max_f32_e32 v49, 0, v49
	v_pk_mul_f32 v[46:47], v[46:47], v[46:47]
	v_pk_mul_f32 v[48:49], v[48:49], v[48:49]
	v_cvt_pk_bf16_f32 v46, v46, v47
	v_cvt_pk_bf16_f32 v47, v48, v49
	ds_write_b64 v236, v[34:35] offset:33344
	ds_write_b64 v236, v[38:39] offset:33360
	ds_write_b64 v236, v[42:43] offset:33376
	ds_write_b64 v236, v[46:47] offset:33392
	v_max_f32_e32 v18, 0, v18
	v_max_f32_e32 v19, 0, v19
	v_max_f32_e32 v20, 0, v20
	v_max_f32_e32 v21, 0, v21
	v_pk_mul_f32 v[18:19], v[18:19], v[18:19]
	v_pk_mul_f32 v[20:21], v[20:21], v[20:21]
	v_cvt_pk_bf16_f32 v18, v18, v19
	v_cvt_pk_bf16_f32 v19, v20, v21
	v_max_f32_e32 v22, 0, v22
	v_max_f32_e32 v23, 0, v23
	v_max_f32_e32 v24, 0, v24
	v_max_f32_e32 v25, 0, v25
	v_pk_mul_f32 v[22:23], v[22:23], v[22:23]
	v_pk_mul_f32 v[24:25], v[24:25], v[24:25]
	v_cvt_pk_bf16_f32 v22, v22, v23
	v_cvt_pk_bf16_f32 v23, v24, v25
	v_max_f32_e32 v26, 0, v26
	v_max_f32_e32 v27, 0, v27
	v_max_f32_e32 v28, 0, v28
	v_max_f32_e32 v29, 0, v29
	v_pk_mul_f32 v[26:27], v[26:27], v[26:27]
	v_pk_mul_f32 v[28:29], v[28:29], v[28:29]
	v_cvt_pk_bf16_f32 v26, v26, v27
	v_cvt_pk_bf16_f32 v27, v28, v29
	v_max_f32_e32 v30, 0, v30
	v_max_f32_e32 v31, 0, v31
	v_max_f32_e32 v32, 0, v32
	v_max_f32_e32 v33, 0, v33
	v_pk_mul_f32 v[30:31], v[30:31], v[30:31]
	v_pk_mul_f32 v[32:33], v[32:33], v[32:33]
	v_cvt_pk_bf16_f32 v30, v30, v31
	v_cvt_pk_bf16_f32 v31, v32, v33
	ds_write_b64 v236, v[18:19] offset:49920
	ds_write_b64 v236, v[22:23] offset:49936
	ds_write_b64 v236, v[26:27] offset:49952
	ds_write_b64 v236, v[30:31] offset:49968
	v_max_f32_e32 v2, 0, v2
	v_max_f32_e32 v3, 0, v3
	v_max_f32_e32 v4, 0, v4
	v_max_f32_e32 v5, 0, v5
	v_pk_mul_f32 v[2:3], v[2:3], v[2:3]
	v_pk_mul_f32 v[4:5], v[4:5], v[4:5]
	v_cvt_pk_bf16_f32 v2, v2, v3
	v_cvt_pk_bf16_f32 v3, v4, v5
	v_max_f32_e32 v6, 0, v6
	v_max_f32_e32 v7, 0, v7
	v_max_f32_e32 v8, 0, v8
	v_max_f32_e32 v9, 0, v9
	v_pk_mul_f32 v[6:7], v[6:7], v[6:7]
	v_pk_mul_f32 v[8:9], v[8:9], v[8:9]
	v_cvt_pk_bf16_f32 v6, v6, v7
	v_cvt_pk_bf16_f32 v7, v8, v9
	v_max_f32_e32 v10, 0, v10
	v_max_f32_e32 v11, 0, v11
	v_max_f32_e32 v12, 0, v12
	v_max_f32_e32 v13, 0, v13
	v_pk_mul_f32 v[10:11], v[10:11], v[10:11]
	v_pk_mul_f32 v[12:13], v[12:13], v[12:13]
	v_cvt_pk_bf16_f32 v10, v10, v11
	v_cvt_pk_bf16_f32 v11, v12, v13
	v_max_f32_e32 v14, 0, v14
	v_max_f32_e32 v15, 0, v15
	v_max_f32_e32 v16, 0, v16
	v_max_f32_e32 v17, 0, v17
	v_pk_mul_f32 v[14:15], v[14:15], v[14:15]
	v_pk_mul_f32 v[16:17], v[16:17], v[16:17]
	v_cvt_pk_bf16_f32 v14, v14, v15
	v_cvt_pk_bf16_f32 v15, v16, v17
	ds_write_b64 v236, v[2:3] offset:49984
	ds_write_b64 v236, v[6:7] offset:50000
	ds_write_b64 v236, v[10:11] offset:50016
	ds_write_b64 v236, v[14:15] offset:50032
	s_waitcnt lgkmcnt(0)
	s_barrier
	s_cmp_eq_u32 s10, 0
	s_cbranch_scc1 .Lg3_nok2_m2
	global_load_dwordx4 v[66:69], v206, s[98:99]
	global_load_dwordx4 v[70:73], v207, s[98:99]
	global_load_dwordx4 v[74:77], v208, s[98:99]
	global_load_dwordx4 v[78:81], v238, s[98:99]
	global_load_dwordx4 v[82:85], v206, s[100:101]
	global_load_dwordx4 v[86:89], v207, s[100:101]
	global_load_dwordx4 v[90:93], v208, s[100:101]
	global_load_dwordx4 v[94:97], v238, s[100:101]
; DI void gemm_phase(const Params& p, int layer, int mode, int nrows, char* lds_all) {
;     ...
;             *(uint4*)((u16*)(p.ws + O_Z) + (size_t)row * HP + col) = o;
.Lg3_nok2_m2:
	v_lshrrev_b32_e32 v237, 5, v165
	v_and_b32_e32 v194, 31, v165
	v_mul_u32_u24_e32 v235, 0x208, v237
	v_lshl_add_u32 v235, v194, 4, v235
	ds_read2_b64 v[2:5], v235 offset1:1
	v_add_u32_e32 v235, 0x2080, v235
	ds_read2_b64 v[6:9], v235 offset1:1
	v_add_u32_e32 v235, 0x2080, v235
	ds_read2_b64 v[10:13], v235 offset1:1
	v_add_u32_e32 v235, 0x2080, v235
	ds_read2_b64 v[14:17], v235 offset1:1
	v_add_u32_e32 v235, 0x2080, v235
	ds_read2_b64 v[18:21], v235 offset1:1
	v_add_u32_e32 v235, 0x2080, v235
	ds_read2_b64 v[22:25], v235 offset1:1
	v_add_u32_e32 v235, 0x2080, v235
	ds_read2_b64 v[26:29], v235 offset1:1
	v_add_u32_e32 v235, 0x2080, v235
	ds_read2_b64 v[30:33], v235 offset1:1
	v_add_u32_e32 v235, 0x2080, v235
	ds_read2_b64 v[34:37], v235 offset1:1
	v_add_u32_e32 v235, 0x2080, v235
	ds_read2_b64 v[38:41], v235 offset1:1
	v_add_u32_e32 v235, 0x2080, v235
	ds_read2_b64 v[42:45], v235 offset1:1
	v_add_u32_e32 v235, 0x2080, v235
	ds_read2_b64 v[46:49], v235 offset1:1
	v_add_u32_e32 v235, 0x2080, v235
	ds_read2_b64 v[50:53], v235 offset1:1
	v_add_u32_e32 v235, 0x2080, v235
	ds_read2_b64 v[54:57], v235 offset1:1
	v_add_u32_e32 v235, 0x2080, v235
	ds_read2_b64 v[58:61], v235 offset1:1
	v_add_u32_e32 v235, 0x2080, v235
	ds_read2_b64 v[62:65], v235 offset1:1
	s_waitcnt lgkmcnt(15)
	global_store_dwordx4 v234, v[2:5], s[50:51]
	v_add_u32_e32 v234, 0x21000, v234
	s_waitcnt lgkmcnt(14)
	global_store_dwordx4 v234, v[6:9], s[50:51]
	v_add_u32_e32 v234, 0x21000, v234
	s_waitcnt lgkmcnt(13)
	global_store_dwordx4 v234, v[10:13], s[50:51]
	v_add_u32_e32 v234, 0x21000, v234
	s_waitcnt lgkmcnt(12)
	global_store_dwordx4 v234, v[14:17], s[50:51]
	v_add_u32_e32 v234, 0x21000, v234
	s_waitcnt lgkmcnt(11)
	global_store_dwordx4 v234, v[18:21], s[50:51]
	v_add_u32_e32 v234, 0x21000, v234
	s_waitcnt lgkmcnt(10)
	global_store_dwordx4 v234, v[22:25], s[50:51]
	v_add_u32_e32 v234, 0x21000, v234
	s_waitcnt lgkmcnt(9)
	global_store_dwordx4 v234, v[26:29], s[50:51]
	v_add_u32_e32 v234, 0x21000, v234
	s_waitcnt lgkmcnt(8)
	global_store_dwordx4 v234, v[30:33], s[50:51]
	v_add_u32_e32 v234, 0x21000, v234
	s_waitcnt lgkmcnt(7)
	global_store_dwordx4 v234, v[34:37], s[50:51]
	v_add_u32_e32 v234, 0x21000, v234
	s_waitcnt lgkmcnt(6)
	global_store_dwordx4 v234, v[38:41], s[50:51]
	v_add_u32_e32 v234, 0x21000, v234
	s_waitcnt lgkmcnt(5)
	global_store_dwordx4 v234, v[42:45], s[50:51]
	v_add_u32_e32 v234, 0x21000, v234
	s_waitcnt lgkmcnt(4)
	global_store_dwordx4 v234, v[46:49], s[50:51]
	v_add_u32_e32 v234, 0x21000, v234
	s_waitcnt lgkmcnt(3)
	global_store_dwordx4 v234, v[50:53], s[50:51]
	v_add_u32_e32 v234, 0x21000, v234
	s_waitcnt lgkmcnt(2)
	global_store_dwordx4 v234, v[54:57], s[50:51]
	v_add_u32_e32 v234, 0x21000, v234
	s_waitcnt lgkmcnt(1)
	global_store_dwordx4 v234, v[58:61], s[50:51]
	v_add_u32_e32 v234, 0x21000, v234
	s_waitcnt lgkmcnt(0)
	global_store_dwordx4 v234, v[62:65], s[50:51]
	s_cmp_lg_u32 s10, 0
	s_cbranch_scc1 .Lg3_start_m2
	v_mov_b32_e32 v190, 0x10c20
	v_mov_b32_e32 v191, 0x11040
	v_mov_b32_e32 v192, 0x11460
	v_mov_b32_e32 v193, 0x12900
	v_mov_b32_e32 v194, 0x12d20
	v_mov_b32_e32 v195, 0x13140
	v_mov_b32_e32 v196, 0x13560
	v_mov_b32_e32 v197, 0x14a00
	v_mov_b32_e32 v198, 0x14e20
	v_mov_b32_e32 v199, 0x15240
	v_mov_b32_e32 v200, 0x15660
	v_mov_b32_e32 v201, 0x16b00
	v_mov_b32_e32 v202, 0x16f20
	v_mov_b32_e32 v203, 0x17340
	v_mov_b32_e32 v204, 0x17760
	v_mov_b32_e32 v205, 0x18c00
	v_mov_b32_e32 v206, 0x19020
	v_mov_b32_e32 v207, 0x19440
	v_mov_b32_e32 v208, 0x10800
	s_branch .LBB0_842
